# attention steady loop: dead pointer advances deleted, x+0 adds turned into s_nop (byte-phase neutral)
# baseline (speedup 1.0000x reference)
; #define WAIT_BAR(N) asm volatile("s_waitcnt vmcnt(" #N ") lgkmcnt(0)\n\ts_barrier" ::: "memory")
; #define RESC() do { if (!FIXM && resc) { asm volatile("s_waitcnt lgkmcnt(0)" ::: "memory"); \
;       _Pragma("unroll") for (int d_ = 0; d_ < 2; ++d_) _Pragma("unroll") for (int r = 0; r < 16; ++r) o[d_][r] *= wsf[crow(r, hi)]; } } while (0)
; #define ROT() do { sl_prev = sl_cur; sl_cur = sl_next; sl_next = (sl_next == (NSLOT - 1) * SLOTB) ? 0 : sl_next + SLOTB; } while (0)
; template <int THRL, bool FIXM> __device__ __forceinline__ bool attn_unit(const h16* Qrows, const h16* __restrict__ Kh, const h16* __restrict__ Vh, const int NT, h16* Yrows, const h16* BZrows, char* shm, const int tid, const float mfix, ...
;     ...
;   int t = 1;
;   for (; t + 5 < NT; t += 2) {
;     STEP(pB0, pB1, pA0, pA1, t, true, true, true);     WAIT_BAR(2); RESC(); ROT();
.LBB0_77:
	v_add_u32_e32 v0, s44, v233
	ds_read_b64_tr_b16 v[62:63], v0 offset:24576
	ds_read_b64_tr_b16 v[64:65], v0 offset:25088
	v_add_f32_e32 v51, v82, v83
	v_add_f32_e32 v51, v84, v51
	v_add_f32_e32 v51, v85, v51
	v_add_f32_e32 v51, v86, v51
	v_add_f32_e32 v51, v87, v51
	v_cvt_pk_f16_f32 v160, v82, v83
	v_cvt_pk_f16_f32 v161, v84, v85
	s_waitcnt lgkmcnt(9)
	v_mfma_f32_32x32x16_f16 v[114:129], v[192:195], v[144:147], v[2:17]
	ds_read_b64_tr_b16 v[82:83], v0 offset:28672
	ds_read_b64_tr_b16 v[84:85], v0 offset:29184
	v_add_f32_e32 v51, v88, v51
	v_add_f32_e32 v51, v89, v51
	v_add_f32_e32 v51, v90, v51
	v_add_f32_e32 v51, v91, v51
	v_cvt_pk_f16_f32 v162, v86, v87
	v_cvt_pk_f16_f32 v163, v88, v89
	s_waitcnt lgkmcnt(10)
	v_mfma_f32_32x32x16_f16 v[98:113], v[188:191], v[144:147], v[2:17]
	ds_read_b64_tr_b16 v[86:87], v0 offset:25600
	ds_read_b64_tr_b16 v[88:89], v0 offset:26112
	v_add_f32_e32 v51, v92, v51
	v_add_f32_e32 v51, v93, v51
	v_add_f32_e32 v51, v94, v51
	v_add_f32_e32 v51, v95, v51
	v_cvt_pk_f16_f32 v156, v90, v91
	v_cvt_pk_f16_f32 v157, v92, v93
	s_waitcnt lgkmcnt(11)
	v_mfma_f32_32x32x16_f16 v[114:129], v[184:187], v[140:143], v[114:129]
	ds_read_b64_tr_b16 v[90:91], v0 offset:29696
	ds_read_b64_tr_b16 v[92:93], v0 offset:30208
	v_add_f32_e32 v51, v96, v51
	v_add_f32_e32 v51, v97, v51
	v_add_f32_e32 v51, v66, v51
	v_add_f32_e32 v51, v67, v51
	v_cvt_pk_f16_f32 v158, v94, v95
	v_cvt_pk_f16_f32 v159, v96, v97
	s_waitcnt lgkmcnt(12)
	v_mfma_f32_32x32x16_f16 v[98:113], v[180:183], v[140:143], v[98:113]
	ds_read_b64_tr_b16 v[94:95], v0 offset:26624
	ds_read_b64_tr_b16 v[96:97], v0 offset:27136
	v_add_f32_e32 v51, v68, v51
	v_add_f32_e32 v51, v69, v51
	v_add_f32_e32 v51, v70, v51
	v_add_f32_e32 v51, v71, v51
	v_cvt_pk_f16_f32 v152, v66, v67
	v_cvt_pk_f16_f32 v153, v68, v69
	s_waitcnt lgkmcnt(13)
	v_mfma_f32_32x32x16_f16 v[114:129], v[176:179], v[136:139], v[114:129]
	ds_read_b64_tr_b16 v[66:67], v0 offset:30720
	ds_read_b64_tr_b16 v[68:69], v0 offset:31232
	v_add_f32_e32 v51, v72, v51
	v_add_f32_e32 v51, v73, v51
	v_add_f32_e32 v51, v74, v51
	v_add_f32_e32 v51, v75, v51
	v_cvt_pk_f16_f32 v154, v70, v71
	v_cvt_pk_f16_f32 v155, v72, v73
	s_waitcnt lgkmcnt(14)
	v_mfma_f32_32x32x16_f16 v[98:113], v[172:175], v[136:139], v[98:113]
	ds_read_b64_tr_b16 v[70:71], v0 offset:27648
	ds_read_b64_tr_b16 v[72:73], v0 offset:28160
	v_add_f32_e32 v51, v76, v51
	v_add_f32_e32 v51, v77, v51
	v_add_f32_e32 v51, v78, v51
	v_add_f32_e32 v51, v79, v51
	v_cvt_pk_f16_f32 v148, v74, v75
	v_cvt_pk_f16_f32 v149, v76, v77
	s_waitcnt lgkmcnt(14)
	v_mfma_f32_32x32x16_f16 v[114:129], v[168:171], v[132:135], v[114:129]
	ds_read_b64_tr_b16 v[74:75], v0 offset:31744
	ds_read_b64_tr_b16 v[76:77], v0 offset:32256
	v_add_f32_e32 v0, v80, v51
	v_add_f32_e32 v0, v81, v0
	s_nop 0
	v_cvt_pk_f16_f32 v150, v78, v79
	v_cvt_pk_f16_f32 v151, v80, v81
	v_mfma_f32_32x32x16_f16 v[98:113], v[164:167], v[132:135], v[98:113]
	v_add_f32_e32 v0, v50, v0
	s_add_i32 s43, s42, s97
	s_mov_b32 s44, m0
	s_mov_b32 m0, s43
	s_nop 0
	global_load_lds_dwordx4 v214, s[100:101]
	s_mov_b32 m0, s44
	s_add_i32 s43, s25, s83
	s_mov_b32 s44, m0
	s_mov_b32 m0, s43
	s_nop 0
	global_load_lds_dwordx4 v208, vcc
	s_mov_b32 m0, s44
	s_add_u32 s100, s100, 0x2000
	s_addc_u32 s101, s101, 0
	s_add_u32 vcc_lo, vcc_lo, 0x2000
	s_addc_u32 vcc_hi, vcc_hi, 0
	s_waitcnt lgkmcnt(14)
	v_mfma_f32_32x32x16_f16 v[18:33], v[160:163], v[62:65], v[18:33]
	v_exp_f32_e32 v114, v114
	v_exp_f32_e32 v115, v115
	v_exp_f32_e32 v116, v116
	v_exp_f32_e32 v117, v117
	s_waitcnt lgkmcnt(12)
	v_mfma_f32_32x32x16_f16 v[34:49], v[160:163], v[82:85], v[34:49]
	v_exp_f32_e32 v118, v118
	v_exp_f32_e32 v119, v119
	v_exp_f32_e32 v120, v120
	v_exp_f32_e32 v121, v121
	v_add_u32_e32 v50, s25, v219
	ds_read_b128 v[62:65], v50
	ds_read_b128 v[164:167], v50 offset:512
	s_waitcnt lgkmcnt(12)
	v_mfma_f32_32x32x16_f16 v[18:33], v[156:159], v[86:89], v[18:33]
	v_exp_f32_e32 v122, v122
	v_exp_f32_e32 v123, v123
	v_exp_f32_e32 v124, v124
	v_exp_f32_e32 v125, v125
	ds_read_b128 v[168:171], v50 offset:2048
	ds_read_b128 v[172:175], v50 offset:2560
	s_waitcnt lgkmcnt(12)
	v_mfma_f32_32x32x16_f16 v[34:49], v[156:159], v[90:93], v[34:49]
	v_exp_f32_e32 v126, v126
	v_exp_f32_e32 v127, v127
	v_exp_f32_e32 v128, v128
	v_exp_f32_e32 v129, v129
	ds_read_b128 v[176:179], v50 offset:4096
	ds_read_b128 v[180:183], v50 offset:4608
	s_waitcnt lgkmcnt(12)
	v_mfma_f32_32x32x16_f16 v[18:33], v[152:155], v[94:97], v[18:33]
	v_exp_f32_e32 v98, v98
	v_exp_f32_e32 v99, v99
	v_exp_f32_e32 v100, v100
	v_exp_f32_e32 v101, v101
	ds_read_b128 v[184:187], v50 offset:6144
	ds_read_b128 v[50:53], v50 offset:6656
	s_waitcnt lgkmcnt(12)
	v_mfma_f32_32x32x16_f16 v[34:49], v[152:155], v[66:69], v[34:49]
	v_exp_f32_e32 v102, v102
	v_exp_f32_e32 v103, v103
	v_exp_f32_e32 v104, v104
	v_exp_f32_e32 v105, v105
	s_waitcnt lgkmcnt(10)
	v_mfma_f32_32x32x16_f16 v[18:33], v[148:151], v[70:73], v[18:33]
	v_exp_f32_e32 v106, v106
	v_exp_f32_e32 v107, v107
	v_exp_f32_e32 v108, v108
	v_exp_f32_e32 v109, v109
	s_waitcnt lgkmcnt(8)
	v_mfma_f32_32x32x16_f16 v[34:49], v[148:151], v[74:77], v[34:49]
	v_exp_f32_e32 v110, v110
	v_exp_f32_e32 v111, v111
	v_exp_f32_e32 v112, v112
	v_exp_f32_e32 v113, v113
	s_waitcnt vmcnt(2) lgkmcnt(8)
	s_barrier
; #define WAIT_BAR(N) asm volatile("s_waitcnt vmcnt(" #N ") lgkmcnt(0)\n\ts_barrier" ::: "memory")
; #define RESC() do { if (!FIXM && resc) { asm volatile("s_waitcnt lgkmcnt(0)" ::: "memory"); \
;       _Pragma("unroll") for (int d_ = 0; d_ < 2; ++d_) _Pragma("unroll") for (int r = 0; r < 16; ++r) o[d_][r] *= wsf[crow(r, hi)]; } } while (0)
; #define ROT() do { sl_prev = sl_cur; sl_cur = sl_next; sl_next = (sl_next == (NSLOT - 1) * SLOTB) ? 0 : sl_next + SLOTB; } while (0)
; template <int THRL, bool FIXM> __device__ __forceinline__ bool attn_unit(const h16* Qrows, const h16* __restrict__ Kh, const h16* __restrict__ Vh, const int NT, h16* Yrows, const h16* BZrows, char* shm, const int tid, const float mfix, ...
;     ...
;   int t = 1;
;   for (; t + 5 < NT; t += 2) {
;     STEP(pB0, pB1, pA0, pA1, t, true, true, true);     WAIT_BAR(2); RESC(); ROT();
;     STEP(pA0, pA1, pB0, pB1, t + 1, true, true, true); WAIT_BAR(2); RESC(); ROT();
	s_add_i32 s43, s25, 0x2000
	s_cmpk_lg_i32 s25, 0x4000
	s_cselect_b32 s43, s43, 0
	v_add_u32_e32 v192, s42, v233
	ds_read_b64_tr_b16 v[188:189], v192 offset:24576
	ds_read_b64_tr_b16 v[190:191], v192 offset:25088
	s_waitcnt lgkmcnt(9)
	v_mfma_f32_32x32x16_f16 v[82:97], v[62:65], v[144:147], v[2:17]
	v_add_f32_e32 v66, v114, v115
	v_add_f32_e32 v66, v116, v66
	v_add_f32_e32 v66, v117, v66
	v_add_f32_e32 v66, v118, v66
	v_add_f32_e32 v66, v119, v66
	v_cvt_pk_f16_f32 v160, v114, v115
	v_cvt_pk_f16_f32 v161, v116, v117
	ds_read_b64_tr_b16 v[62:63], v192 offset:28672
	ds_read_b64_tr_b16 v[64:65], v192 offset:29184
	v_add_f32_e32 v66, v120, v66
	v_add_f32_e32 v66, v121, v66
	v_add_f32_e32 v66, v122, v66
	v_add_f32_e32 v148, v123, v66
	s_waitcnt lgkmcnt(10)
	v_mfma_f32_32x32x16_f16 v[66:81], v[164:167], v[144:147], v[2:17]
	v_cvt_pk_f16_f32 v162, v118, v119
	v_cvt_pk_f16_f32 v163, v120, v121
	ds_read_b64_tr_b16 v[114:115], v192 offset:25600
	ds_read_b64_tr_b16 v[116:117], v192 offset:26112
	s_waitcnt lgkmcnt(11)
	v_mfma_f32_32x32x16_f16 v[82:97], v[168:171], v[140:143], v[82:97]
	v_add_f32_e32 v118, v124, v148
	v_add_f32_e32 v118, v125, v118
	v_add_f32_e32 v118, v126, v118
	v_add_f32_e32 v148, v127, v118
	v_cvt_pk_f16_f32 v156, v122, v123
	v_cvt_pk_f16_f32 v157, v124, v125
	ds_read_b64_tr_b16 v[118:119], v192 offset:29696
	ds_read_b64_tr_b16 v[120:121], v192 offset:30208
	s_waitcnt lgkmcnt(12)
	v_mfma_f32_32x32x16_f16 v[66:81], v[172:175], v[140:143], v[66:81]
	v_add_f32_e32 v122, v128, v148
	v_add_f32_e32 v122, v129, v122
	v_add_f32_e32 v122, v98, v122
	v_add_f32_e32 v148, v99, v122
	v_cvt_pk_f16_f32 v158, v126, v127
	v_cvt_pk_f16_f32 v159, v128, v129
	ds_read_b64_tr_b16 v[122:123], v192 offset:26624
	ds_read_b64_tr_b16 v[124:125], v192 offset:27136
	s_waitcnt lgkmcnt(13)
	v_mfma_f32_32x32x16_f16 v[82:97], v[176:179], v[136:139], v[82:97]
	v_add_f32_e32 v126, v100, v148
	v_add_f32_e32 v126, v101, v126
	v_add_f32_e32 v126, v102, v126
	v_add_f32_e32 v126, v103, v126
	v_cvt_pk_f16_f32 v152, v98, v99
	v_cvt_pk_f16_f32 v153, v100, v101
	ds_read_b64_tr_b16 v[98:99], v192 offset:30720
	ds_read_b64_tr_b16 v[100:101], v192 offset:31232
	s_waitcnt lgkmcnt(14)
	v_mfma_f32_32x32x16_f16 v[66:81], v[180:183], v[136:139], v[66:81]
	v_add_f32_e32 v126, v104, v126
	v_add_f32_e32 v126, v105, v126
	v_add_f32_e32 v126, v106, v126
	v_add_f32_e32 v126, v107, v126
	v_cvt_pk_f16_f32 v154, v102, v103
	v_cvt_pk_f16_f32 v155, v104, v105
	ds_read_b64_tr_b16 v[102:103], v192 offset:27648
	ds_read_b64_tr_b16 v[104:105], v192 offset:28160
	s_waitcnt lgkmcnt(14)
	v_mfma_f32_32x32x16_f16 v[82:97], v[184:187], v[132:135], v[82:97]
	v_add_f32_e32 v126, v108, v126
	v_add_f32_e32 v126, v109, v126
	v_add_f32_e32 v126, v110, v126
	v_add_f32_e32 v126, v111, v126
	v_cvt_pk_f16_f32 v148, v106, v107
	v_cvt_pk_f16_f32 v149, v108, v109
	ds_read_b64_tr_b16 v[106:107], v192 offset:31744
	ds_read_b64_tr_b16 v[108:109], v192 offset:32256
	v_mfma_f32_32x32x16_f16 v[66:81], v[50:53], v[132:135], v[66:81]
	v_add_f32_e32 v50, v112, v126
	v_add_f32_e32 v50, v113, v50
	s_nop 0
	v_cvt_pk_f16_f32 v150, v110, v111
	v_cvt_pk_f16_f32 v151, v112, v113
	s_add_i32 s42, s25, s97
	s_mov_b32 s44, m0
	s_mov_b32 m0, s42
	s_nop 0
	global_load_lds_dwordx4 v214, s[100:101]
	s_mov_b32 m0, s44
	s_add_i32 s42, s43, s83
	s_mov_b32 s44, m0
	s_mov_b32 m0, s42
	s_nop 0
	global_load_lds_dwordx4 v208, vcc
	s_mov_b32 m0, s44
	s_add_u32 s100, s100, 0x2000
	s_addc_u32 s101, s101, 0
	s_add_u32 vcc_lo, vcc_lo, 0x2000
	s_addc_u32 vcc_hi, vcc_hi, 0
	v_add_f32_e32 v50, v0, v50
	s_waitcnt lgkmcnt(14)
	v_mfma_f32_32x32x16_f16 v[18:33], v[160:163], v[188:191], v[18:33]
	v_exp_f32_e32 v82, v82
	v_exp_f32_e32 v83, v83
	v_exp_f32_e32 v84, v84
	v_exp_f32_e32 v85, v85
	s_waitcnt lgkmcnt(12)
	v_mfma_f32_32x32x16_f16 v[34:49], v[160:163], v[62:65], v[34:49]
	v_exp_f32_e32 v86, v86
	v_exp_f32_e32 v87, v87
	v_exp_f32_e32 v88, v88
	v_exp_f32_e32 v89, v89
	v_add_u32_e32 v0, s43, v219
	ds_read_b128 v[192:195], v0
	ds_read_b128 v[188:191], v0 offset:512
	s_waitcnt lgkmcnt(12)
	v_mfma_f32_32x32x16_f16 v[18:33], v[156:159], v[114:117], v[18:33]
	v_exp_f32_e32 v90, v90
	v_exp_f32_e32 v91, v91
	v_exp_f32_e32 v92, v92
	v_exp_f32_e32 v93, v93
	ds_read_b128 v[184:187], v0 offset:2048
	ds_read_b128 v[180:183], v0 offset:2560
	s_waitcnt lgkmcnt(12)
	v_mfma_f32_32x32x16_f16 v[34:49], v[156:159], v[118:121], v[34:49]
	v_exp_f32_e32 v94, v94
	v_exp_f32_e32 v95, v95
	v_exp_f32_e32 v96, v96
	v_exp_f32_e32 v97, v97
	ds_read_b128 v[176:179], v0 offset:4096
	ds_read_b128 v[172:175], v0 offset:4608
	s_waitcnt lgkmcnt(12)
	v_mfma_f32_32x32x16_f16 v[18:33], v[152:155], v[122:125], v[18:33]
	v_exp_f32_e32 v66, v66
	v_exp_f32_e32 v67, v67
	v_exp_f32_e32 v68, v68
	v_exp_f32_e32 v69, v69
	ds_read_b128 v[168:171], v0 offset:6144
	ds_read_b128 v[164:167], v0 offset:6656
	s_waitcnt lgkmcnt(12)
	v_mfma_f32_32x32x16_f16 v[34:49], v[152:155], v[98:101], v[34:49]
	v_exp_f32_e32 v70, v70
	v_exp_f32_e32 v71, v71
	v_exp_f32_e32 v72, v72
	v_exp_f32_e32 v73, v73
	s_waitcnt lgkmcnt(10)
	v_mfma_f32_32x32x16_f16 v[18:33], v[148:151], v[102:105], v[18:33]
	v_exp_f32_e32 v74, v74
	v_exp_f32_e32 v75, v75
	v_exp_f32_e32 v76, v76
	v_exp_f32_e32 v77, v77
	s_waitcnt lgkmcnt(8)
	v_mfma_f32_32x32x16_f16 v[34:49], v[148:151], v[106:109], v[34:49]
	v_exp_f32_e32 v78, v78
	v_exp_f32_e32 v79, v79
	v_exp_f32_e32 v80, v80
	v_exp_f32_e32 v81, v81
	s_add_i32 s45, s43, 0x2000
	s_waitcnt vmcnt(2) lgkmcnt(8)
	s_barrier
	s_cmpk_lg_i32 s43, 0x4000
	s_mov_b32 s44, s25
	s_cselect_b32 s25, s45, 0
	s_add_i32 s24, s24, 2
	s_mov_b32 s42, s43
	s_cmp_lt_u32 s24, 29
	s_cbranch_scc1 .LBB0_77
	s_mov_b64 s[36:37], 0x10c84000
	s_mov_b64 s[60:61], 0x10388000
	s_mov_b32 s45, 31
	s_branch .LBB0_80
